# post1 token loop: token row (45 ushort loads) prefetched one token ahead into a second register set
# baseline (speedup 1.0000x reference)
.LBB0_600:
	s_andn2_b64 vcc, exec, s[0:1]
	s_cbranch_vccnz .LBB0_669
	v_readlane_b32 s0, v254, 3
	v_readlane_b32 s1, v254, 4
	v_mov_b32_e32 v3, v206
	s_andn2_b64 vcc, exec, s[0:1]
	s_cbranch_vccnz .LBB0_660
	v_ashrrev_i32_e32 v38, 6, v3
	v_lshlrev_b32_e32 v0, 1, v38
	v_and_b32_e32 v53, 8, v0
	v_and_b32_e32 v0, 15, v3
	v_cvt_f32_ubyte0_e32 v0, v0
	v_mul_f32_e32 v4, 0xbf549a78, v0
	s_mov_b32 s0, 0xc2fc0000
	v_readlane_b32 s4, v254, 53
	v_cmp_gt_f32_e32 vcc, s0, v4
	v_mov_b32_e32 v4, 0x42800000
	v_readlane_b32 s5, v254, 54
	v_cndmask_b32_e32 v4, 0, v4, vcc
	v_fmac_f32_e32 v4, 0xbf549a78, v0
	s_and_b64 s[0:1], s[4:5], exec
	v_and_b32_e32 v2, 63, v3
	v_exp_f32_e32 v0, v4
	s_cselect_b32 s0, 64, 0
	v_or_b32_e32 v26, s0, v2
	s_cselect_b32 s0, 0x180, 0
	v_not_b32_e32 v4, 63
	v_or_b32_e32 v30, s0, v2
	s_cselect_b32 s0, 0x80, 0
	v_cndmask_b32_e32 v4, 0, v4, vcc
	v_or_b32_e32 v32, s0, v2
	v_readlane_b32 s0, v254, 17
	v_ldexp_f32 v54, v0, v4
	v_lshlrev_b32_e32 v0, 2, v2
	v_readlane_b32 s1, v254, 18
	v_readlane_b32 s36, v252, 1
	v_and_b32_e32 v8, 16, v3
	v_lshl_add_u64 v[4:5], s[0:1], 0, v[0:1]
	v_readlane_b32 s0, v254, 15
	v_readlane_b32 s37, v252, 2
	v_readlane_b32 s38, v252, 3
	v_readlane_b32 s39, v252, 4
	v_readlane_b32 s40, v252, 5
	v_readlane_b32 s41, v252, 6
	v_readlane_b32 s42, v252, 7
	v_readlane_b32 s43, v252, 8
	v_readlane_b32 s44, v252, 9
	v_readlane_b32 s45, v252, 10
	v_readlane_b32 s46, v252, 11
	v_readlane_b32 s47, v252, 12
	v_readlane_b32 s48, v252, 13
	v_readlane_b32 s49, v252, 14
	v_readlane_b32 s50, v252, 15
	v_readlane_b32 s51, v252, 16
	v_cndmask_b32_e64 v52, 0, 1, s[4:5]
	v_readlane_b32 s1, v254, 16
	v_cmp_eq_u32_e64 s[4:5], 0, v8
	v_lshl_add_u64 v[8:9], s[44:45], 0, v[0:1]
	v_lshl_add_u64 v[10:11], s[46:47], 0, v[0:1]
	v_readlane_b32 s36, v253, 17
	v_lshl_add_u64 v[6:7], s[0:1], 0, v[0:1]
	v_lshlrev_b32_e32 v0, 1, v2
	v_readlane_b32 s37, v253, 18
	v_readlane_b32 s38, v253, 19
	v_readlane_b32 s39, v253, 20
	v_readlane_b32 s40, v253, 21
	v_readlane_b32 s41, v253, 22
	v_readlane_b32 s42, v253, 23
	v_readlane_b32 s43, v253, 24
	v_readlane_b32 s44, v253, 25
	v_readlane_b32 s45, v253, 26
	v_readlane_b32 s46, v253, 27
	v_readlane_b32 s47, v253, 28
	v_readlane_b32 s48, v253, 29
	v_readlane_b32 s49, v253, 30
	v_readlane_b32 s50, v253, 31
	v_readlane_b32 s51, v253, 32
	s_waitcnt vmcnt(0)
	v_lshl_add_u64 v[14:15], s[46:47], 0, v[0:1]
	v_lshl_add_u64 v[16:17], s[48:49], 0, v[0:1]
	v_lshl_add_u64 v[18:19], s[40:41], 0, v[0:1]
	v_lshl_add_u64 v[22:23], s[44:45], 0, v[0:1]
	v_lshl_add_u64 v[24:25], s[38:39], 0, v[0:1]
	v_readlane_b32 s36, v252, 17
	v_lshl_add_u64 v[12:13], s[94:95], 0, v[0:1]
	v_lshl_add_u64 v[20:21], s[90:91], 0, v[0:1]
	v_lshlrev_b32_e32 v0, 2, v26
	v_readlane_b32 s37, v252, 18
	v_readlane_b32 s38, v252, 19
	v_readlane_b32 s39, v252, 20
	v_readlane_b32 s40, v252, 21
	v_readlane_b32 s41, v252, 22
	v_readlane_b32 s42, v252, 23
	v_readlane_b32 s43, v252, 24
	v_readlane_b32 s44, v252, 25
	v_readlane_b32 s45, v252, 26
	v_readlane_b32 s46, v252, 27
	v_readlane_b32 s47, v252, 28
	v_readlane_b32 s48, v252, 29
	v_readlane_b32 s49, v252, 30
	v_readlane_b32 s50, v252, 31
	v_readlane_b32 s51, v252, 32
	v_lshlrev_b32_e32 v30, 2, v30
	v_mov_b32_e32 v31, v1
	v_lshl_add_u64 v[26:27], s[50:51], 0, v[0:1]
	v_readlane_b32 s36, v252, 33
	v_readlane_b32 s37, v252, 34
	v_readlane_b32 s38, v252, 35
	v_readlane_b32 s39, v252, 36
	v_readlane_b32 s40, v252, 37
	v_readlane_b32 s41, v252, 38
	v_readlane_b32 s42, v252, 39
	v_readlane_b32 s43, v252, 40
	v_readlane_b32 s44, v252, 41
	v_readlane_b32 s45, v252, 42
	v_readlane_b32 s46, v252, 43
	v_readlane_b32 s47, v252, 44
	v_readlane_b32 s48, v252, 45
	v_readlane_b32 s49, v252, 46
	v_readlane_b32 s50, v252, 47
	v_readlane_b32 s51, v252, 48
	v_lshlrev_b32_e32 v32, 2, v32
	v_mov_b32_e32 v33, v1
	v_lshl_add_u64 v[28:29], s[36:37], 0, v[0:1]
	v_lshl_add_u64 v[30:31], s[40:41], 0, v[30:31]
	v_lshl_add_u64 v[32:33], s[44:45], 0, v[32:33]
	v_readlane_b32 s36, v252, 49
	v_readlane_b32 s37, v252, 50
	v_readlane_b32 s38, v252, 51
	v_readlane_b32 s39, v252, 52
	v_readlane_b32 s0, v254, 42
	v_cmp_gt_u32_e32 vcc, 32, v2
	v_mul_u32_u24_e32 v55, 0x3800, v2
	v_lshl_add_u64 v[34:35], s[36:37], 0, v[0:1]
	v_lshl_add_u64 v[36:37], s[38:39], 0, v[0:1]
	v_add_u32_e32 v38, s0, v38
	v_readlane_b32 s52, v252, 0
	v_readlane_b32 s40, v252, 53
	v_readlane_b32 s41, v252, 54
	v_readlane_b32 s42, v252, 55
	v_readlane_b32 s43, v252, 56
	v_readlane_b32 s44, v252, 57
	v_readlane_b32 s45, v252, 58
	v_readlane_b32 s46, v252, 59
	v_readlane_b32 s47, v252, 60
	v_readlane_b32 s48, v252, 61
	v_readlane_b32 s49, v252, 62
	v_readlane_b32 s50, v252, 63
	v_readlane_b32 s51, v253, 0
	global_load_dword v108, v[26:27], off
	global_load_dword v109, v[28:29], off
	global_load_dword v110, v[30:31], off
	global_load_dword v111, v[30:31], off offset:256
	global_load_dword v112, v[30:31], off offset:512
	global_load_dword v113, v[30:31], off offset:768
	global_load_dword v114, v[30:31], off offset:1024
	global_load_dword v115, v[30:31], off offset:1280
	global_load_dword v116, v[32:33], off
	global_load_dword v117, v[32:33], off offset:256
	global_load_dword v118, v[34:35], off
	global_load_dword v119, v[36:37], off
	s_waitcnt vmcnt(0)
	s_movk_i32 s0, 0x3000
	v_cmp_gt_i32_e64 s[10:11], s0, v38
	s_and_saveexec_b64 s[0:1], s[10:11]
	s_cbranch_execz .Lpf1_pre
	s_movk_i32 s6, 0x1c00
	v_mad_i64_i32 v[166:167], s[10:11], v38, s6, v[20:21]
	global_load_ushort v120, v[166:167], off
	global_load_ushort v121, v[166:167], off offset:128
	global_load_ushort v122, v[166:167], off offset:256
	global_load_ushort v123, v[166:167], off offset:384
	global_load_ushort v124, v[166:167], off offset:512
	global_load_ushort v125, v[166:167], off offset:640
	global_load_ushort v126, v[166:167], off offset:768
	global_load_ushort v127, v[166:167], off offset:896
	global_load_ushort v128, v[166:167], off offset:1024
	global_load_ushort v129, v[166:167], off offset:1152
	global_load_ushort v130, v[166:167], off offset:1280
	global_load_ushort v131, v[166:167], off offset:1408
	global_load_ushort v132, v[166:167], off offset:1536
	global_load_ushort v133, v[166:167], off offset:1664
	global_load_ushort v134, v[166:167], off offset:1792
	global_load_ushort v135, v[166:167], off offset:1920
	global_load_ushort v136, v[166:167], off offset:2048
	global_load_ushort v137, v[166:167], off offset:2176
	global_load_ushort v138, v[166:167], off offset:2304
	global_load_ushort v139, v[166:167], off offset:2432
	global_load_ushort v140, v[166:167], off offset:2560
	global_load_ushort v141, v[166:167], off offset:2688
	global_load_ushort v142, v[166:167], off offset:2816
	global_load_ushort v143, v[166:167], off offset:2944
	global_load_ushort v144, v[166:167], off offset:3072
	global_load_ushort v145, v[166:167], off offset:3200
	global_load_ushort v146, v[166:167], off offset:3328
	global_load_ushort v147, v[166:167], off offset:3456
	global_load_ushort v148, v[166:167], off offset:3584
	global_load_ushort v149, v[166:167], off offset:3712
	global_load_ushort v150, v[166:167], off offset:3840
	global_load_ushort v151, v[166:167], off offset:3968
	s_movk_i32 s6, 0x1000
	v_add_co_u32_e64 v166, s[10:11], s6, v166
	s_nop 1
	v_addc_co_u32_e64 v167, s[10:11], 0, v167, s[10:11]
	global_load_ushort v152, v[166:167], off
	global_load_ushort v153, v[166:167], off offset:128
	global_load_ushort v154, v[166:167], off offset:256
	global_load_ushort v155, v[166:167], off offset:384
	global_load_ushort v156, v[166:167], off offset:512
	global_load_ushort v157, v[166:167], off offset:640
	global_load_ushort v158, v[166:167], off offset:768
	global_load_ushort v159, v[166:167], off offset:896
	global_load_ushort v160, v[166:167], off offset:1024
	global_load_ushort v161, v[166:167], off offset:1152
	global_load_ushort v162, v[166:167], off offset:1280
	global_load_ushort v163, v[166:167], off offset:1408
	global_load_ushort v164, v[166:167], off offset:1536
.Lpf1_pre:
	s_or_b64 exec, exec, s[0:1]
	s_branch .LBB0_605

.LBB0_607:
	s_andn2_saveexec_b64 s[72:73], s[6:7]
	s_cbranch_execz .LBB0_604
	s_waitcnt vmcnt(0)
	v_mov_b32_e32 v44, v120
	v_mov_b32_e32 v100, v121
	v_mov_b32_e32 v97, v122
	v_mov_b32_e32 v94, v123
	v_mov_b32_e32 v90, v124
	v_mov_b32_e32 v86, v125
	v_mov_b32_e32 v83, v126
	v_mov_b32_e32 v80, v127
	v_mov_b32_e32 v102, v128
	v_mov_b32_e32 v99, v129
	v_mov_b32_e32 v96, v130
	v_mov_b32_e32 v93, v131
	v_mov_b32_e32 v88, v132
	v_mov_b32_e32 v85, v133
	v_mov_b32_e32 v82, v134
	v_mov_b32_e32 v79, v135
	v_mov_b32_e32 v101, v136
	v_mov_b32_e32 v98, v137
	v_mov_b32_e32 v95, v138
	v_mov_b32_e32 v92, v139
	v_mov_b32_e32 v87, v140
	v_mov_b32_e32 v84, v141
	v_mov_b32_e32 v81, v142
	v_mov_b32_e32 v78, v143
	v_mov_b32_e32 v76, v144
	v_mov_b32_e32 v77, v145
	v_mov_b32_e32 v74, v146
	v_mov_b32_e32 v75, v147
	v_mov_b32_e32 v72, v148
	v_mov_b32_e32 v73, v149
	v_mov_b32_e32 v70, v150
	v_mov_b32_e32 v71, v151
	v_mov_b32_e32 v69, v152
	v_mov_b32_e32 v68, v153
	v_mov_b32_e32 v67, v154
	v_mov_b32_e32 v66, v155
	v_mov_b32_e32 v65, v156
	v_mov_b32_e32 v64, v157
	v_mov_b32_e32 v63, v158
	v_mov_b32_e32 v62, v159
	v_mov_b32_e32 v61, v160
	v_mov_b32_e32 v59, v161
	v_mov_b32_e32 v57, v162
	v_mov_b32_e32 v58, v163
	v_mov_b32_e32 v56, v164
	v_readlane_b32 s0, v254, 43
	s_nop 3
	v_add_u32_e32 v165, s0, v38
	s_movk_i32 s0, 0x3000
	v_cmp_gt_i32_e64 s[10:11], s0, v165
	s_and_saveexec_b64 s[0:1], s[10:11]
	s_cbranch_execz .Lpf1_loop
	s_movk_i32 s6, 0x1c00
	v_mad_i64_i32 v[166:167], s[10:11], v165, s6, v[20:21]
	global_load_ushort v120, v[166:167], off
	global_load_ushort v121, v[166:167], off offset:128
	global_load_ushort v122, v[166:167], off offset:256
	global_load_ushort v123, v[166:167], off offset:384
	global_load_ushort v124, v[166:167], off offset:512
	global_load_ushort v125, v[166:167], off offset:640
	global_load_ushort v126, v[166:167], off offset:768
	global_load_ushort v127, v[166:167], off offset:896
	global_load_ushort v128, v[166:167], off offset:1024
	global_load_ushort v129, v[166:167], off offset:1152
	global_load_ushort v130, v[166:167], off offset:1280
	global_load_ushort v131, v[166:167], off offset:1408
	global_load_ushort v132, v[166:167], off offset:1536
	global_load_ushort v133, v[166:167], off offset:1664
	global_load_ushort v134, v[166:167], off offset:1792
	global_load_ushort v135, v[166:167], off offset:1920
	global_load_ushort v136, v[166:167], off offset:2048
	global_load_ushort v137, v[166:167], off offset:2176
	global_load_ushort v138, v[166:167], off offset:2304
	global_load_ushort v139, v[166:167], off offset:2432
	global_load_ushort v140, v[166:167], off offset:2560
	global_load_ushort v141, v[166:167], off offset:2688
	global_load_ushort v142, v[166:167], off offset:2816
	global_load_ushort v143, v[166:167], off offset:2944
	global_load_ushort v144, v[166:167], off offset:3072
	global_load_ushort v145, v[166:167], off offset:3200
	global_load_ushort v146, v[166:167], off offset:3328
	global_load_ushort v147, v[166:167], off offset:3456
	global_load_ushort v148, v[166:167], off offset:3584
	global_load_ushort v149, v[166:167], off offset:3712
	global_load_ushort v150, v[166:167], off offset:3840
	global_load_ushort v151, v[166:167], off offset:3968
	s_movk_i32 s6, 0x1000
	v_add_co_u32_e64 v166, s[10:11], s6, v166
	s_nop 1
	v_addc_co_u32_e64 v167, s[10:11], 0, v167, s[10:11]
	global_load_ushort v152, v[166:167], off
	global_load_ushort v153, v[166:167], off offset:128
	global_load_ushort v154, v[166:167], off offset:256
	global_load_ushort v155, v[166:167], off offset:384
	global_load_ushort v156, v[166:167], off offset:512
	global_load_ushort v157, v[166:167], off offset:640
	global_load_ushort v158, v[166:167], off offset:768
	global_load_ushort v159, v[166:167], off offset:896
	global_load_ushort v160, v[166:167], off offset:1024
	global_load_ushort v161, v[166:167], off offset:1152
	global_load_ushort v162, v[166:167], off offset:1280
	global_load_ushort v163, v[166:167], off offset:1408
	global_load_ushort v164, v[166:167], off offset:1536
.Lpf1_loop:
	s_or_b64 exec, exec, s[0:1]
	s_movk_i32 s0, 0x1000
	v_cmp_gt_i32_e64 s[8:9], s0, v38
	s_movk_i32 s0, 0xfff
	v_cmp_lt_i32_e64 s[6:7], s0, v38
	s_and_saveexec_b64 s[0:1], s[6:7]
	s_xor_b64 s[76:77], exec, s[0:1]
	s_cbranch_execz .LBB0_614
	v_bfe_u32 v0, v38, 6, 5
	v_and_b32_e32 v39, 63, v38
	v_cndmask_b32_e32 v0, v39, v0, vcc
	v_cvt_f32_ubyte0_e32 v0, v0
	v_mul_f32_e32 v39, v54, v0
	s_brev_b32 s0, 18
	v_cmp_ngt_f32_e64 s[10:11], s0, v39
	s_and_saveexec_b64 s[0:1], s[10:11]
	s_xor_b64 s[0:1], exec, s[0:1]
	s_cbranch_execz .LBB0_611
	v_lshrrev_b32_e32 v0, 23, v39
	v_add_u32_e32 v0, 0xffffff88, v0
	v_cmp_lt_u32_e64 s[10:11], 63, v0
	v_not_b32_e32 v40, 63
	v_not_b32_e32 v41, 31
	v_cndmask_b32_e64 v40, 0, v40, s[10:11]
	v_add_u32_e32 v0, v40, v0
	v_cmp_lt_u32_e64 s[12:13], 31, v0
	s_mov_b32 s16, 0xfe5163ab
	s_nop 0
	v_cndmask_b32_e64 v40, 0, v41, s[12:13]
	v_add_u32_e32 v0, v40, v0
	v_cmp_lt_u32_e64 s[14:15], 31, v0
	s_nop 1
	v_cndmask_b32_e64 v40, 0, v41, s[14:15]
	v_add_u32_e32 v45, v40, v0
	v_and_b32_e32 v0, 0x7fffff, v39
	v_or_b32_e32 v60, 0x800000, v0
	v_mad_u64_u32 v[40:41], s[16:17], v60, s16, 0
	v_mov_b32_e32 v0, v41
	s_mov_b32 s16, 0x3c439041
	v_mad_u64_u32 v[42:43], s[16:17], v60, s16, v[0:1]
	v_mov_b32_e32 v0, v43
	s_mov_b32 s16, 0xdb629599
	v_mad_u64_u32 v[46:47], s[16:17], v60, s16, v[0:1]
	v_mov_b32_e32 v0, v47
	s_mov_b32 s16, 0xf534ddc0
	v_mad_u64_u32 v[48:49], s[16:17], v60, s16, v[0:1]
	v_mov_b32_e32 v0, v49
	s_mov_b32 s16, 0xfc2757d1
	v_mad_u64_u32 v[50:51], s[16:17], v60, s16, v[0:1]
	v_mov_b32_e32 v0, v51
	s_mov_b32 s16, 0x4e441529
	v_mad_u64_u32 v[104:105], s[16:17], v60, s16, v[0:1]
	v_mov_b32_e32 v0, v105
	s_mov_b32 s16, 0xa2f9836e
	v_mad_u64_u32 v[106:107], s[16:17], v60, s16, v[0:1]
	v_cndmask_b32_e64 v41, v104, v48, s[10:11]
	v_cndmask_b32_e64 v0, v106, v50, s[10:11]
	v_cndmask_b32_e64 v47, v107, v104, s[10:11]
	v_cndmask_b32_e64 v43, v0, v41, s[12:13]
	v_cndmask_b32_e64 v0, v47, v0, s[12:13]
	v_cndmask_b32_e64 v47, v50, v46, s[10:11]
	v_cndmask_b32_e64 v41, v41, v47, s[12:13]
	v_cndmask_b32_e64 v0, v0, v43, s[14:15]
	v_cndmask_b32_e64 v43, v43, v41, s[14:15]
	v_sub_u32_e32 v49, 32, v45
	v_alignbit_b32 v50, v0, v43, v49
	v_cmp_eq_u32_e64 s[16:17], 0, v45
	v_cndmask_b32_e64 v40, v46, v40, s[10:11]
	s_nop 0
	v_cndmask_b32_e64 v45, v50, v0, s[16:17]
	v_cndmask_b32_e64 v0, v48, v42, s[10:11]
	v_cndmask_b32_e64 v42, v47, v0, s[12:13]
	v_cndmask_b32_e64 v41, v41, v42, s[14:15]
	v_alignbit_b32 v47, v43, v41, v49
	v_cndmask_b32_e64 v43, v47, v43, s[16:17]
	v_bfe_u32 v50, v45, 29, 1
	v_cndmask_b32_e64 v0, v0, v40, s[12:13]
	v_alignbit_b32 v47, v45, v43, 30
	v_sub_u32_e32 v51, 0, v50
	v_cndmask_b32_e64 v0, v42, v0, s[14:15]
	v_xor_b32_e32 v47, v47, v51
	v_alignbit_b32 v40, v41, v0, v49
	v_cndmask_b32_e64 v40, v40, v41, s[16:17]
	v_ffbh_u32_e32 v42, v47
	v_alignbit_b32 v41, v43, v40, 30
	v_min_u32_e32 v42, 32, v42
	v_alignbit_b32 v0, v40, v0, 30
	v_xor_b32_e32 v41, v41, v51
	v_sub_u32_e32 v43, 31, v42
	v_xor_b32_e32 v0, v0, v51
	v_alignbit_b32 v46, v47, v41, v43
	v_alignbit_b32 v0, v41, v0, v43
	v_alignbit_b32 v40, v46, v0, 9
	v_ffbh_u32_e32 v41, v40
	v_min_u32_e32 v41, 32, v41
	v_lshrrev_b32_e32 v48, 29, v45
	v_not_b32_e32 v43, v41
	v_alignbit_b32 v0, v40, v0, v43
	v_lshlrev_b32_e32 v40, 31, v48
	v_or_b32_e32 v43, 0x33000000, v40
	v_add_lshl_u32 v41, v41, v42, 23
	v_lshrrev_b32_e32 v0, 9, v0
	v_sub_u32_e32 v41, v43, v41
	v_or_b32_e32 v40, 0.5, v40
	v_lshlrev_b32_e32 v42, 23, v42
	v_or_b32_e32 v0, v41, v0
	v_lshrrev_b32_e32 v41, 9, v46
	v_sub_u32_e32 v40, v40, v42
	v_or_b32_e32 v40, v41, v40
	v_mul_f32_e32 v41, 0x3fc90fda, v40
	s_mov_b32 s10, 0x3fc90fda
	v_fma_f32 v42, v40, s10, -v41
	v_fmac_f32_e32 v42, 0x33a22168, v40
	v_fmac_f32_e32 v42, 0x3fc90fda, v0
	v_lshrrev_b32_e32 v40, 30, v45
	v_add_f32_e32 v0, v41, v42
	v_add_u32_e32 v40, v50, v40

.LBB0_614:
	s_or_saveexec_b64 s[0:1], s[76:77]
	v_mov_b64_e32 v[40:41], 0
	s_xor_b64 exec, exec, s[0:1]
	v_ashrrev_i32_e32 v0, 7, v38
	v_and_or_b32 v40, v0, -2, v52
	v_ashrrev_i32_e32 v41, 31, v40
	v_lshlrev_b64 v[40:41], 8, v[40:41]
	s_movk_i32 s10, 0xff
	v_and_or_b32 v40, v38, s10, v40
	v_mov_b32_e32 v0, 1.0
	v_mov_b32_e32 v60, 0
	s_or_b64 exec, exec, s[0:1]
	v_mov_b32_e32 v91, v108
	v_mov_b32_e32 v89, v109
	v_lshlrev_b32_e32 v44, 16, v44
	v_mul_f32_e32 v45, v44, v44
	v_mov_b32_e32 v46, v1
	s_mov_b32 s1, 0x800000
	v_ashrrev_i32_e32 v39, 31, v38
	v_mov_b32_dpp v46, v45 quad_perm:[1,0,3,2] row_mask:0xf bank_mask:0xf
	v_fmac_f32_e32 v46, v44, v44
	v_lshlrev_b32_e32 v102, 16, v102
	v_mov_b32_e32 v104, v1
	v_add_f32_dpp v45, v46, v46 quad_perm:[2,3,0,1] row_mask:0xf bank_mask:0xf bound_ctrl:1
	v_mov_b32_e32 v46, v1
	v_lshlrev_b64 v[42:43], 9, v[40:41]
	v_add_f32_dpp v45, v45, v45 row_half_mirror row_mask:0xf bank_mask:0xf bound_ctrl:1
	v_or_b32_e32 v50, v42, v2
	v_mov_b32_e32 v51, v43
	v_add_f32_dpp v45, v45, v45 row_mirror row_mask:0xf bank_mask:0xf bound_ctrl:1
	v_lshlrev_b64 v[50:51], 2, v[50:51]
	s_nop 0
	v_mov_b32_dpp v46, v45 row_bcast:15 row_mask:0xa bank_mask:0xf
	v_add_f32_e32 v45, v45, v46
	v_mov_b32_e32 v46, v1
	s_nop 1
	v_mov_b32_dpp v46, v45 row_bcast:31 row_mask:0xc bank_mask:0xf
	v_add_f32_e32 v45, v45, v46
	s_nop 0
	v_readlane_b32 s0, v45, 63
	s_nop 1
	v_fma_f32 v45, s0, v208, v209
	v_cmp_gt_f32_e64 s[10:11], s1, v45
	v_mul_f32_e32 v46, 0x4b800000, v45
	s_nop 0
	v_cndmask_b32_e64 v45, v45, v46, s[10:11]
	v_rsq_f32_e32 v45, v45
	s_nop 0
	v_mul_f32_e32 v46, 0x45800000, v45
	v_cndmask_b32_e64 v45, v45, v46, s[10:11]
	v_mul_f32_e32 v44, v45, v44
	v_mul_f32_e32 v44, v91, v44
	v_mul_f32_e32 v44, 0x3e38aa3b, v44
	v_cvt_pk_bf16_f32 v103, v44, s0
	v_lshlrev_b64 v[44:45], 10, v[38:39]
	v_lshl_or_b32 v48, v2, 1, v44
	v_mov_b32_e32 v49, v45
	v_lshl_add_u64 v[46:47], s[92:93], 0, v[48:49]
	global_store_short v[46:47], v103, off
	v_mul_f32_e32 v103, v102, v102
	v_lshl_add_u64 v[48:49], s[94:95], 0, v[48:49]
	s_nop 0
	v_mov_b32_dpp v104, v103 quad_perm:[1,0,3,2] row_mask:0xf bank_mask:0xf
	v_fmac_f32_e32 v104, v102, v102
	s_nop 1
	v_add_f32_dpp v103, v104, v104 quad_perm:[2,3,0,1] row_mask:0xf bank_mask:0xf bound_ctrl:1
	v_mov_b32_e32 v104, v1
	s_nop 0
	v_add_f32_dpp v103, v103, v103 row_half_mirror row_mask:0xf bank_mask:0xf bound_ctrl:1
	s_nop 1
	v_add_f32_dpp v103, v103, v103 row_mirror row_mask:0xf bank_mask:0xf bound_ctrl:1
	s_nop 1
	v_mov_b32_dpp v104, v103 row_bcast:15 row_mask:0xa bank_mask:0xf
	v_add_f32_e32 v103, v103, v104
	v_mov_b32_e32 v104, v1
	s_nop 1
	v_mov_b32_dpp v104, v103 row_bcast:31 row_mask:0xc bank_mask:0xf
	v_add_f32_e32 v103, v103, v104
	s_nop 0
	v_readlane_b32 s0, v103, 63
	s_nop 1
	v_fma_f32 v103, s0, v208, v209
	v_cmp_gt_f32_e64 s[10:11], s1, v103
	v_mul_f32_e32 v104, 0x4b800000, v103
	s_nop 0
	v_cndmask_b32_e64 v103, v103, v104, s[10:11]
	v_rsq_f32_e32 v103, v103
	s_nop 0
	v_mul_f32_e32 v104, 0x45800000, v103
	v_cndmask_b32_e64 v103, v103, v104, s[10:11]
	v_mul_f32_e32 v102, v103, v102
	v_mul_f32_e32 v102, v89, v102
	v_cvt_pk_bf16_f32 v103, v102, s0
	global_store_short v[48:49], v103, off
	s_and_saveexec_b64 s[0:1], s[8:9]
	s_cbranch_execz .LBB0_618
	v_readlane_b32 s10, v254, 7
	v_readlane_b32 s11, v254, 8
	v_lshlrev_b32_e32 v101, 16, v101
	s_nop 0
	v_lshl_add_u64 v[104:105], s[10:11], 0, v[50:51]
	v_readlane_b32 s10, v254, 9
	v_readlane_b32 s11, v254, 10
	s_nop 1
	v_lshl_add_u64 v[106:107], s[10:11], 0, v[50:51]
	global_store_dword v[104:105], v102, off
	global_store_dword v[106:107], v101, off
